# sample differential-attention tile loop: both f32 K/V chunk load groups issued together (second group into spare registers), counted vmcnt
# speedup vs baseline: 1.0181x; 1.0064x over previous
; #define LAS __attribute__((address_space(3)))
; __device__ __forceinline__ unsigned pk2(float lo, float hi) { return f2bf(lo) | (f2bf(hi) << 16); }
; template <bool DIFF, bool FIXED, bool F32SRC> ...
;     ...
;         if (F32SRC) {
; #pragma unroll
;             for (int i = 0; i < NCH; ++i) {
;                 const int c = tid + 512 * i, row = c / (HW / 8), ch = c % (HW / 8);
;                 const size_t so = (j == u.jhi) ? (size_t)min(row, 15) * PITCH + u.h * HW + ch * 8 : (size_t)(64 * j + row) * PITCH + u.h * HW + ch * 8;
;                 const float* ks_ = ((j == u.jhi) ? kn : kc) + so; const float* vs_ = ((j == u.jhi) ? vn : vc) + so;
;                 const f32x4 k0 = ((const f32x4*)ks_)[0], k1 = ((const f32x4*)ks_)[1], v0 = ((const f32x4*)vs_)[0], v1 = ((const f32x4*)vs_)[1];
;                 u32x4 kw, vw; kw.x = pk2(k0.x, k0.y); kw.y = pk2(k0.z, k0.w); kw.z = pk2(k1.x, k1.y); kw.w = pk2(k1.z, k1.w); vw.x = pk2(v0.x, v0.y); vw.y = pk2(v0.z, v0.w); vw.z = pk2(v1.x, v1.y); vw.w = pk2(v1.z, v1.w);
;                 *(LAS u32x4*)(lds + buf * BUF + row * RB + ((ch ^ (DIFF ? (row & 15) : ((row >> 1) & 7))) << 4)) = kw;
;                 *(LAS u32x4*)(lds + buf * BUF + KBUF + (row >> 3) * (NDB * 512) + (ch >> 2) * 512 + (row & 7) * 64 + (ch & 3) * 16) = vw;
;             }
;             __syncthreads();
;         } else {
;         const int b2 = (buf >= 1) ? buf - 1 : 2;
;         if (j - 2 >= u.jlo) ATT_DMA(j - 2, b2);
;         }
;         const bool comp = (wact && j <= cq && j >= cq - win);
;         if (comp) {
;             const LAS unsigned char* kb = lds + buf * BUF; const LAS unsigned char* vb = kb + KBUF;
;             const int dqi = qloc - 64 * j - 4 * hi; const float dq = (float)dqi;
;             bf16x8 kf0[2], kf1[2];
; #pragma unroll
;             for (int ks = 0; ks < 2; ++ks) { kf0[ks] = *(const LAS bf16x8*)(kb + koff[ks]); kf1[ks] = *(const LAS bf16x8*)(kb + koff[ks] + 32 * RB); }
.LBB0_447:
	s_lshl_b32 s0, s59, 15
	s_add_i32 s64, s0, 0
	s_cmpk_eq_i32 s60, 0x800
	s_cselect_b64 vcc, -1, 0
	v_add_u32_e32 v0, s60, v222
	v_cndmask_b32_e32 v66, v0, v223, vcc
	v_ashrrev_i32_e32 v67, 31, v66
	v_lshlrev_b64 v[66:67], 10, v[66:67]
	s_and_b64 s[0:1], vcc, exec
	v_lshl_add_u64 v[66:67], v[134:135], 0, v[66:67]
	s_cselect_b32 s1, s58, s29
	s_cselect_b32 s0, s51, s28
	s_cselect_b32 s17, s50, s25
	s_cselect_b32 s16, s30, s24
	v_lshlrev_b64 v[66:67], 2, v[66:67]
	v_lshl_add_u64 v[70:71], s[16:17], 0, v[66:67]
	v_lshl_add_u64 v[78:79], s[0:1], 0, v[66:67]
	global_load_dwordx4 v[66:69], v[70:71], off offset:16
	s_nop 0
	global_load_dwordx4 v[70:73], v[70:71], off
	s_nop 0
	global_load_dwordx4 v[74:77], v[78:79], off offset:16
	s_nop 0
	global_load_dwordx4 v[78:81], v[78:79], off
	v_add_u32_e32 v114, s60, v230
	v_cndmask_b32_e32 v114, v114, v231, vcc
	v_ashrrev_i32_e32 v115, 31, v114
	v_lshlrev_b64 v[114:115], 10, v[114:115]
	v_lshl_add_u64 v[114:115], v[136:137], 0, v[114:115]
	v_lshlrev_b64 v[114:115], 2, v[114:115]
	v_lshl_add_u64 v[116:117], s[16:17], 0, v[114:115]
	v_lshl_add_u64 v[118:119], s[0:1], 0, v[114:115]
	global_load_dwordx4 v[82:85], v[116:117], off offset:16
	global_load_dwordx4 v[86:89], v[116:117], off
	global_load_dwordx4 v[90:93], v[118:119], off offset:16
	global_load_dwordx4 v[94:97], v[118:119], off
	s_cmp_le_i32 s61, s62
	s_waitcnt vmcnt(4)
	v_bfe_u32 v0, v70, 16, 1
	v_add3_u32 v0, v70, v0, s31
	v_bfe_u32 v70, v71, 16, 1
	v_lshrrev_b32_e32 v0, 16, v0
	v_add3_u32 v70, v71, v70, s31
	v_and_or_b32 v70, v70, s77, v0
	v_bfe_u32 v0, v72, 16, 1
	v_add3_u32 v0, v72, v0, s31
	v_bfe_u32 v71, v73, 16, 1
	v_lshrrev_b32_e32 v0, 16, v0
	v_add3_u32 v71, v73, v71, s31
	v_and_or_b32 v71, v71, s77, v0
	v_bfe_u32 v0, v66, 16, 1
	v_add3_u32 v0, v66, v0, s31
	v_bfe_u32 v66, v67, 16, 1
	v_lshrrev_b32_e32 v0, 16, v0
	v_add3_u32 v66, v67, v66, s31
	v_and_or_b32 v72, v66, s77, v0
	v_bfe_u32 v0, v68, 16, 1
	v_add3_u32 v0, v68, v0, s31
	v_bfe_u32 v66, v69, 16, 1
	v_lshrrev_b32_e32 v0, 16, v0
	v_add3_u32 v66, v69, v66, s31
	v_and_or_b32 v73, v66, s77, v0
	v_bfe_u32 v0, v78, 16, 1
	v_add3_u32 v0, v78, v0, s31
	v_bfe_u32 v66, v79, 16, 1
	v_lshrrev_b32_e32 v0, 16, v0
	v_add3_u32 v66, v79, v66, s31
	v_and_or_b32 v66, v66, s77, v0
	v_bfe_u32 v0, v80, 16, 1
	v_add3_u32 v0, v80, v0, s31
	v_bfe_u32 v67, v81, 16, 1
	v_lshrrev_b32_e32 v0, 16, v0
	v_add3_u32 v67, v81, v67, s31
	v_and_or_b32 v67, v67, s77, v0
	v_bfe_u32 v0, v74, 16, 1
	v_add3_u32 v0, v74, v0, s31
	v_bfe_u32 v68, v75, 16, 1
	v_lshrrev_b32_e32 v0, 16, v0
	v_add3_u32 v68, v75, v68, s31
	v_and_or_b32 v68, v68, s77, v0
	v_bfe_u32 v0, v76, 16, 1
	v_add3_u32 v0, v76, v0, s31
	v_bfe_u32 v69, v77, 16, 1
	v_lshrrev_b32_e32 v0, 16, v0
	v_add3_u32 v69, v77, v69, s31
	v_and_or_b32 v69, v69, s77, v0
	v_add3_u32 v0, s64, v224, v225
	ds_write_b128 v0, v[70:73]
	v_add3_u32 v0, s64, v226, v227
	v_add3_u32 v0, v0, v228, v229
	ds_write_b128 v0, v[66:69] offset:16384
	s_cselect_b64 s[0:1], -1, 0
	s_and_b64 s[0:1], s[12:13], s[0:1]
	s_cmp_ge_i32 s61, s63
	s_cselect_b64 s[16:17], -1, 0
	s_and_b64 s[0:1], s[0:1], s[16:17]
	s_andn2_b64 vcc, exec, s[0:1]
	s_waitcnt vmcnt(0)
	v_bfe_u32 v0, v86, 16, 1
	v_add3_u32 v0, v86, v0, s31
	v_bfe_u32 v86, v87, 16, 1
	v_lshrrev_b32_e32 v0, 16, v0
	v_add3_u32 v86, v87, v86, s31
	v_and_or_b32 v86, v86, s77, v0
	v_bfe_u32 v0, v88, 16, 1
	v_add3_u32 v0, v88, v0, s31
	v_bfe_u32 v87, v89, 16, 1
	v_lshrrev_b32_e32 v0, 16, v0
	v_add3_u32 v87, v89, v87, s31
	v_and_or_b32 v87, v87, s77, v0
	v_bfe_u32 v0, v82, 16, 1
	v_add3_u32 v0, v82, v0, s31
	v_bfe_u32 v82, v83, 16, 1
	v_lshrrev_b32_e32 v0, 16, v0
	v_add3_u32 v82, v83, v82, s31
	v_and_or_b32 v88, v82, s77, v0
	v_bfe_u32 v0, v84, 16, 1
	v_add3_u32 v0, v84, v0, s31
	v_bfe_u32 v82, v85, 16, 1
	v_lshrrev_b32_e32 v0, 16, v0
	v_add3_u32 v82, v85, v82, s31
	v_and_or_b32 v89, v82, s77, v0
	v_bfe_u32 v0, v94, 16, 1
	v_add3_u32 v0, v94, v0, s31
	v_bfe_u32 v82, v95, 16, 1
	v_lshrrev_b32_e32 v0, 16, v0
	v_add3_u32 v82, v95, v82, s31
	v_and_or_b32 v82, v82, s77, v0
	v_bfe_u32 v0, v96, 16, 1
	v_add3_u32 v0, v96, v0, s31
	v_bfe_u32 v83, v97, 16, 1
	v_lshrrev_b32_e32 v0, 16, v0
	v_add3_u32 v83, v97, v83, s31
	v_and_or_b32 v83, v83, s77, v0
	v_bfe_u32 v0, v90, 16, 1
	v_add3_u32 v0, v90, v0, s31
	v_bfe_u32 v90, v91, 16, 1
	v_lshrrev_b32_e32 v0, 16, v0
	v_add3_u32 v90, v91, v90, s31
	v_and_or_b32 v84, v90, s77, v0
	v_bfe_u32 v0, v92, 16, 1
	v_add3_u32 v0, v92, v0, s31
	v_bfe_u32 v90, v93, 16, 1
	v_lshrrev_b32_e32 v0, 16, v0
	v_add3_u32 v90, v93, v90, s31
	v_and_or_b32 v85, v90, s77, v0
	v_add3_u32 v0, s64, v232, v233
	ds_write_b128 v0, v[86:89]
	v_add3_u32 v0, s64, v234, v235
	v_add3_u32 v0, v0, v236, v237
	ds_write_b128 v0, v[82:85] offset:16384
	s_waitcnt lgkmcnt(0)
	s_barrier
	s_cbranch_vccnz .LBB0_446
	v_add3_u32 v0, s64, v194, v193
	ds_read_b128 v[126:129], v0
	ds_read_b128 v[118:121], v0 offset:8192
	v_add3_u32 v0, s64, v195, v193
	ds_read_b128 v[122:125], v0
	ds_read_b128 v[114:117], v0 offset:8192
	v_cvt_f32_i32_e32 v0, v238
	s_cmp_lt_u32 s61, s62
	s_mov_b64 s[0:1], -1
	s_cbranch_scc0 .LBB0_454
	s_andn2_b64 vcc, exec, s[0:1]
	s_cbranch_vccz .LBB0_455
